# GEMM phase prologues (QKV, q_b/kv_b, gate/up, O-proj, down): the first-tile wait and its barrier moved from the end of the prologue to just before the first K iteration, so the first unit's scheduler
# baseline (speedup 1.0000x reference)
.LBB0_421:
	s_add_u32 s14, s20, 0x1be12000
	s_addc_u32 s15, s21, 0
	v_bfe_u32 v17, v10, 4, 2
	s_add_u32 s16, s20, 0x2bb32000
	v_and_b32_e32 v214, 15, v10
	v_lshlrev_b32_e32 v0, 4, v17
	v_lshlrev_b32_e32 v19, 2, v10
	s_addc_u32 s17, s21, 0
	v_lshl_or_b32 v18, v214, 6, v0
	s_lshl_b32 s7, s19, 13
	v_and_b32_e32 v19, 32, v19
	v_bitop3_b32 v20, v18, s7, v19 bitop3:0xde
	s_lshl_b32 s7, s22, 5
	s_and_b32 s72, s7, 0x60
	s_add_i32 m0, s87, 0x18000
	v_lshl_add_u64 v[8:9], v[8:9], 0, s[54:55]
	s_lshl_b32 s71, s19, 6
	s_lshl_b32 s7, s72, 7
	s_waitcnt vmcnt(2)
	s_barrier
	global_load_lds_dwordx4 v[8:9], off
	v_lshl_add_u64 v[6:7], v[6:7], 0, s[54:55]
	s_add_i32 m0, s87, 0x1a000
	s_add_i32 s73, s87, 0x8000
	s_add_i32 s89, s87, 0xa000
	global_load_lds_dwordx4 v[6:7], off
	v_lshl_add_u64 v[2:3], v[2:3], 0, s[54:55]
	s_mov_b32 m0, s73
	s_add_u32 s22, s34, 0x20080
	global_load_lds_dwordx4 v[2:3], off
	v_lshl_add_u64 v[2:3], v[4:5], 0, s[54:55]
	s_mov_b32 m0, s89
	s_addc_u32 s23, s35, 0
	global_load_lds_dwordx4 v[2:3], off
	s_add_i32 m0, s87, 0x1c000
	v_lshl_add_u64 v[2:3], s[22:23], 0, v[194:195]
	global_load_lds_dwordx4 v[2:3], off
	v_lshl_add_u64 v[2:3], s[22:23], 0, v[196:197]
	s_add_i32 m0, s87, 0x1e000
	v_and_b32_e32 v4, 16, v0
	global_load_lds_dwordx4 v[2:3], off
	v_lshl_add_u64 v[6:7], s[20:21], 0, v[0:1]
	v_lshlrev_b32_e32 v0, 13, v14
	v_and_b32_e32 v0, 0xffffc000, v0
	v_lshl_add_u32 v0, v15, 10, v0
	v_and_b32_e32 v3, 1, v14
	v_lshl_or_b32 v0, v3, 6, v0
	v_lshl_add_u32 v208, v16, 1, v0
	v_lshlrev_b32_e32 v0, 13, v11
	v_and_b32_e32 v0, 0xffffc000, v0
	v_lshrrev_b32_e32 v2, 2, v10
	s_mov_b64 s[20:21], 0x610000
	v_lshl_add_u32 v0, v12, 10, v0
	v_and_b32_e32 v3, 1, v11
	s_cmpk_lt_u32 s18, 0x100
	v_and_b32_e32 v2, 8, v2
	v_lshl_add_u64 v[198:199], v[6:7], 0, s[20:21]
	s_mov_b64 s[20:21], 0x611000
	v_lshl_or_b32 v0, v3, 6, v0
	v_or_b32_e32 v215, s71, v214
	v_bitop3_b32 v216, v18, s7, v19 bitop3:0xde
	s_cselect_b64 s[18:19], -1, 0
	v_or_b32_e32 v217, 16, v214
	v_or_b32_e32 v218, 32, v214
	v_or_b32_e32 v219, 48, v214
	v_lshl_or_b32 v220, v17, 3, s72
	v_lshl_add_u64 v[200:201], v[6:7], 0, s[20:21]
	v_mov_b32_e32 v209, v1
	v_lshl_add_u32 v210, v13, 1, v0
	v_mov_b32_e32 v211, v1
	s_mov_b32 s65, 0
	v_add_u32_e32 v221, 0, v20
	s_lshl_b32 s20, s72, 1
	v_lshlrev_b32_e32 v0, 1, v2
	v_lshlrev_b32_e32 v212, 1, v4
	s_branch .LBB0_424

.LBB0_429:
	s_ashr_i32 s27, s26, 31
	s_lshl_b64 s[28:29], s[26:27], 18
	s_cmp_eq_u32 s44, 0
	s_cselect_b32 s9, s79, s83
	s_cselect_b32 s7, s80, s84
	s_cselect_b32 s21, s81, s77
	s_cselect_b32 s27, s82, s85
	s_add_u32 s28, s9, s28
	s_addc_u32 s29, s7, s29
	s_and_b64 s[30:31], s[22:23], exec
	s_cselect_b32 s7, s29, s37
	s_cselect_b32 s9, s28, s36
	s_ashr_i32 s25, s24, 31
	s_lshl_b64 s[30:31], s[24:25], 18
	s_add_u32 s30, s21, s30
	s_addc_u32 s31, s27, s31
	s_and_b64 s[38:39], s[22:23], exec
	s_cselect_b32 s21, s31, s35
	s_cselect_b32 s25, s30, s34
	s_add_u32 s27, s34, 0x100
	s_addc_u32 s45, s35, 0
	s_add_u32 s34, s36, 0x20080
	s_addc_u32 s35, s37, 0
	s_mov_b32 s48, -2
	s_cmp_eq_u32 s99, 0
	s_cbranch_scc0 .Lnofw_G67
	s_waitcnt vmcnt(6)
	s_barrier

.LBB0_599:
	s_add_u32 s18, s14, 0x1be12000
	s_addc_u32 s19, s15, 0
	s_add_u32 s20, s14, 0x1ee12000
	s_addc_u32 s21, s15, 0
	s_add_u32 s22, s14, 0x1f612000
	s_addc_u32 s23, s15, 0
	s_add_u32 s24, s4, 0x4000000
	s_addc_u32 s25, s5, 0
	s_add_u32 s26, s4, 0x5000000
	s_addc_u32 s27, s5, 0
	s_and_b32 s4, s6, 3
	s_add_i32 m0, s61, 0x18000
	v_lshl_add_u64 v[8:9], v[8:9], 0, s[54:55]
	s_lshl_b32 s33, s7, 6
	s_lshl_b32 s6, s7, 13
	s_lshl_b32 s7, s4, 5
	s_lshl_b32 s11, s4, 12
	s_waitcnt vmcnt(2)
	s_barrier
	global_load_lds_dwordx4 v[8:9], off
	v_lshl_add_u64 v[6:7], v[6:7], 0, s[54:55]
	s_add_i32 m0, s61, 0x1a000
	s_add_i32 s48, s61, 0x8000
	s_add_i32 s49, s61, 0xa000
	global_load_lds_dwordx4 v[6:7], off
	v_lshl_add_u64 v[2:3], v[2:3], 0, s[54:55]
	s_mov_b32 m0, s48
	s_add_u32 s4, s8, 0x80080
	global_load_lds_dwordx4 v[2:3], off
	v_lshl_add_u64 v[2:3], v[4:5], 0, s[54:55]
	s_mov_b32 m0, s49
	s_addc_u32 s5, s9, 0
	global_load_lds_dwordx4 v[2:3], off
	s_add_i32 m0, s61, 0x1c000
	v_lshl_add_u64 v[2:3], s[4:5], 0, v[194:195]
	global_load_lds_dwordx4 v[2:3], off
	v_lshl_add_u64 v[2:3], s[4:5], 0, v[196:197]
	s_add_i32 m0, s61, 0x1e000
	v_and_b32_e32 v227, 15, v10
	global_load_lds_dwordx4 v[2:3], off
	v_bfe_u32 v2, v10, 4, 2
	v_lshlrev_b32_e32 v0, 4, v2
	v_lshlrev_b32_e32 v4, 2, v10
	v_lshl_or_b32 v3, v227, 6, v0
	v_and_b32_e32 v4, 32, v4
	v_bitop3_b32 v5, v3, s6, v4 bitop3:0xde
	v_bitop3_b32 v228, v3, s11, v4 bitop3:0xde
	v_and_b32_e32 v4, 16, v0
	v_lshl_add_u64 v[6:7], s[14:15], 0, v[0:1]
	v_lshlrev_b32_e32 v0, 15, v14
	v_and_b32_e32 v0, 0xffff0000, v0
	v_lshl_add_u32 v0, v15, 12, v0
	v_and_b32_e32 v3, 1, v14
	v_lshl_or_b32 v0, v3, 6, v0
	v_lshl_add_u32 v208, v16, 1, v0
	v_lshlrev_b32_e32 v0, 15, v11
	s_cmpk_lt_u32 s30, 0x100
	v_and_b32_e32 v0, 0xffff0000, v0
	s_cselect_b64 s[28:29], -1, 0
	v_lshlrev_b32_e32 v2, 2, v2
	s_bitcmp0_b32 s30, 6
	s_mov_b64 s[30:31], 0x610000
	v_lshl_add_u32 v0, v12, 12, v0
	v_and_b32_e32 v3, 1, v11
	v_or_b32_e32 v229, s7, v2
	v_and_b32_e32 v2, 8, v2
	v_lshl_add_u64 v[198:199], v[6:7], 0, s[30:31]
	s_mov_b64 s[30:31], 0x611000
	v_lshl_or_b32 v0, v3, 6, v0
	s_mov_b32 s93, 0
	s_cselect_b64 s[4:5], -1, 0
	v_or_b32_e32 v230, 16, v227
	v_or_b32_e32 v231, 32, v227
	v_or_b32_e32 v232, 48, v227
	v_lshl_add_u64 v[200:201], v[6:7], 0, s[30:31]
	v_mov_b32_e32 v209, v1
	v_lshl_add_u32 v210, v13, 1, v0
	v_mov_b32_e32 v211, v1
	v_add_u32_e32 v233, 0, v5
	s_lshl_b32 s94, s7, 1
	v_lshlrev_b32_e32 v0, 1, v2
	v_lshlrev_b32_e32 v212, 1, v4
	s_branch .LBB0_602

.LBB0_604:
	s_ashr_i32 s35, s34, 31
	s_lshl_b64 s[36:37], s[34:35], 20
	s_add_u32 s36, s73, s36
	s_addc_u32 s37, s89, s37
	s_and_b64 s[38:39], s[6:7], exec
	s_cselect_b32 s11, s37, s81
	s_cselect_b32 s35, s36, s80
	s_ashr_i32 s31, s30, 31
	s_lshl_b64 s[38:39], s[30:31], 20
	s_add_u32 s38, s97, s38
	s_addc_u32 s39, s65, s39
	s_and_b64 s[82:83], s[6:7], exec
	s_cselect_b32 s31, s39, s9
	s_cselect_b32 s79, s38, s8
	s_add_u32 s84, s8, 0x100
	s_addc_u32 s85, s9, 0
	s_add_u32 s8, s80, 0x80080
	s_addc_u32 s9, s81, 0
	s_mov_b32 s86, -2
	s_cmp_eq_u32 s99, 0
	s_cbranch_scc0 .Lnofw_G1
	s_waitcnt vmcnt(6)
	s_barrier

.LBB0_877:
	v_lshl_add_u64 v[10:11], s[36:37], 0, v[0:1]
	v_mov_b32_e32 v131, v1
	v_and_b32_e32 v221, 15, v212
	v_and_b32_e32 v18, 48, v212
	v_lshlrev_b32_e32 v19, 2, v212
	v_lshl_add_u64 v[12:13], s[36:37], 0, v[130:131]
	s_and_b32 s33, s19, 3
	s_lshl_b32 s4, s7, 13
	v_lshl_or_b32 v18, v221, 6, v18
	v_and_b32_e32 v19, 32, v19
	s_add_i32 m0, s21, 0x18000
	v_lshl_add_u64 v[10:11], v[10:11], 0, s[54:55]
	v_lshl_add_u64 v[14:15], s[24:25], 0, v[0:1]
	s_lshl_b32 s80, s7, 6
	v_bitop3_b32 v20, v18, s4, v19 bitop3:0xde
	s_lshl_b32 s4, s33, 12
	s_waitcnt vmcnt(2)
	s_barrier
	global_load_lds_dwordx4 v[10:11], off
	v_lshl_add_u64 v[10:11], v[12:13], 0, s[54:55]
	s_add_i32 m0, s21, 0x1a000
	s_add_i32 s68, s21, 0x8000
	s_add_i32 s69, s21, 0xa000
	v_lshl_add_u64 v[16:17], s[24:25], 0, v[130:131]
	v_bitop3_b32 v140, v18, s4, v19 bitop3:0xde
	global_load_lds_dwordx4 v[10:11], off
	v_lshl_add_u64 v[10:11], v[14:15], 0, s[54:55]
	s_mov_b32 m0, s68
	s_add_u32 s4, s36, 0x80080
	global_load_lds_dwordx4 v[10:11], off
	v_lshl_add_u64 v[10:11], v[16:17], 0, s[54:55]
	s_mov_b32 m0, s69
	s_addc_u32 s5, s37, 0
	global_load_lds_dwordx4 v[10:11], off
	s_add_i32 m0, s21, 0x1c000
	v_lshl_add_u64 v[10:11], s[4:5], 0, v[0:1]
	global_load_lds_dwordx4 v[10:11], off
	v_lshl_add_u64 v[10:11], s[4:5], 0, v[130:131]
	s_add_i32 m0, s21, 0x1e000
	v_lshlrev_b32_e32 v2, 14, v2
	global_load_lds_dwordx4 v[10:11], off
	v_lshlrev_b32_e32 v6, 14, v6
	v_and_b32_e32 v2, 0x7fff8000, v2
	v_and_b32_e32 v6, 0x7fff8000, v6
	v_lshl_add_u32 v2, v3, 11, v2
	v_lshl_add_u32 v6, v7, 11, v6
	v_or_b32_e32 v2, v2, v4
	v_or_b32_e32 v6, v6, v8
	v_add_lshl_u32 v134, v2, v5, 1
	s_sext_i32_i8 s18, s6
	v_or_b32_e32 v211, s80, v221
	v_add_lshl_u32 v132, v6, v9, 1
	v_mov_b32_e32 v133, v1
	v_mov_b32_e32 v135, v1
	s_mov_b32 s70, 0
	v_add_u32_e32 v141, 0, v20

.LBB0_884:
	s_add_u32 s72, s36, 0x100
	s_addc_u32 s73, s37, 0
	s_ashr_i32 s29, s28, 31
	s_lshl_b64 s[30:31], s[28:29], 20
	s_add_u32 s34, s82, s30
	s_addc_u32 s35, s83, s31
	s_and_b64 s[30:31], s[6:7], exec
	s_cselect_b32 s29, s35, s25
	s_cselect_b32 s81, s34, s24
	s_ashr_i32 s27, s26, 31
	s_lshl_b64 s[30:31], s[26:27], 20
	s_add_u32 s30, s84, s30
	s_addc_u32 s31, s85, s31
	s_and_b64 s[38:39], s[6:7], exec
	s_cselect_b32 s27, s31, s37
	s_cselect_b32 s86, s30, s36
	s_add_u32 s36, s24, 0x80080
	s_addc_u32 s37, s25, 0
	v_lshl_add_u64 v[136:137], s[36:37], 0, v[132:133]
	v_lshl_add_u64 v[138:139], s[36:37], 0, v[134:135]
	s_mov_b32 s87, -2
	s_mov_b64 s[36:37], 0
	s_waitcnt vmcnt(6)
	s_barrier

.LBB0_939:
	v_lshl_add_u64 v[8:9], s[38:39], 0, v[0:1]
	v_mov_b32_e32 v115, v1
	v_and_b32_e32 v221, 15, v220
	v_and_b32_e32 v16, 48, v220
	v_lshlrev_b32_e32 v17, 2, v220
	v_lshl_add_u64 v[10:11], s[38:39], 0, v[114:115]
	s_and_b32 s33, s17, 3
	s_lshl_b32 s4, s28, 13
	v_lshl_or_b32 v16, v221, 6, v16
	v_and_b32_e32 v17, 32, v17
	s_add_i32 m0, s19, 0x18000
	v_lshl_add_u64 v[8:9], v[8:9], 0, s[54:55]
	v_lshl_add_u64 v[12:13], s[26:27], 0, v[0:1]
	s_lshl_b32 s86, s28, 6
	v_bitop3_b32 v18, v16, s4, v17 bitop3:0xde
	s_lshl_b32 s4, s33, 12
	s_waitcnt vmcnt(2)
	s_barrier
	global_load_lds_dwordx4 v[8:9], off
	v_lshl_add_u64 v[8:9], v[10:11], 0, s[54:55]
	s_add_i32 m0, s19, 0x1a000
	s_add_i32 s68, s19, 0x8000
	s_add_i32 s69, s19, 0xa000
	v_lshl_add_u64 v[14:15], s[26:27], 0, v[114:115]
	v_bitop3_b32 v124, v16, s4, v17 bitop3:0xde
	global_load_lds_dwordx4 v[8:9], off
	v_lshl_add_u64 v[8:9], v[12:13], 0, s[54:55]
	s_mov_b32 m0, s68
	s_add_u32 s4, s38, 0x80080
	global_load_lds_dwordx4 v[8:9], off
	v_lshl_add_u64 v[8:9], v[14:15], 0, s[54:55]
	s_mov_b32 m0, s69
	s_addc_u32 s5, s39, 0
	global_load_lds_dwordx4 v[8:9], off
	s_add_i32 m0, s19, 0x1c000
	v_lshl_add_u64 v[8:9], s[4:5], 0, v[0:1]
	global_load_lds_dwordx4 v[8:9], off
	v_lshl_add_u64 v[8:9], s[4:5], 0, v[114:115]
	s_add_i32 m0, s19, 0x1e000
	s_sext_i32_i8 s16, s16
	global_load_lds_dwordx4 v[8:9], off
	v_lshlrev_b32_e32 v8, 15, v5
	v_and_b32_e32 v8, 0xffff0000, v8
	v_lshl_add_u32 v6, v6, 12, v8
	v_and_b32_e32 v5, 1, v5
	v_lshl_or_b32 v5, v5, 6, v6
	v_lshl_add_u32 v116, v7, 1, v5
	v_lshlrev_b32_e32 v5, 15, v2
	v_and_b32_e32 v5, 0xffff0000, v5
	v_lshl_add_u32 v3, v3, 12, v5
	v_and_b32_e32 v2, 1, v2
	v_lshl_or_b32 v2, v2, 6, v3
	v_lshl_add_u32 v118, v4, 1, v2
	v_or_b32_e32 v151, s86, v221
	v_mov_b32_e32 v117, v1
	v_mov_b32_e32 v119, v1
	s_mov_b32 s70, 0
	v_add_u32_e32 v125, 0, v18

.LBB0_946:
	s_add_u32 s72, s38, 0x100
	s_addc_u32 s73, s39, 0
	s_ashr_i32 s31, s30, 31
	s_lshl_b64 s[34:35], s[30:31], 20
	s_add_u32 s36, s82, s34
	s_addc_u32 s37, s83, s35
	s_and_b64 s[34:35], s[6:7], exec
	s_cselect_b32 s31, s37, s27
	s_cselect_b32 s87, s36, s26
	s_ashr_i32 s29, s28, 31
	s_lshl_b64 s[34:35], s[28:29], 20
	s_add_u32 s34, s84, s34
	s_addc_u32 s35, s85, s35
	s_and_b64 s[78:79], s[6:7], exec
	s_cselect_b32 s29, s35, s39
	s_cselect_b32 s88, s34, s38
	s_add_u32 s38, s26, 0x80080
	s_addc_u32 s39, s27, 0
	v_lshl_add_u64 v[120:121], s[38:39], 0, v[116:117]
	v_lshl_add_u64 v[122:123], s[38:39], 0, v[118:119]
	s_mov_b32 s89, -2
	s_mov_b64 s[38:39], 0
	s_waitcnt vmcnt(6)
	s_barrier

.LBB0_1054:
	v_lshrrev_b32_e32 v18, 1, v16
	v_and_b32_e32 v18, 24, v18
	s_add_u32 s10, s6, 0x22012000
	v_and_b32_e32 v17, 15, v16
	v_lshlrev_b32_e32 v19, 1, v18
	v_lshlrev_b32_e32 v16, 2, v16
	s_sext_i32_i16 s25, s4
	s_addc_u32 s11, s7, 0
	v_lshl_or_b32 v137, s15, 6, v17
	v_lshl_or_b32 v17, v17, 6, v19
	s_lshl_b32 s4, s15, 13
	v_and_b32_e32 v16, 32, v16
	v_bitop3_b32 v19, v17, s4, v16 bitop3:0xde
	s_lshl_b32 s4, s14, 5
	s_and_b32 s4, s4, 0x60
	s_add_i32 m0, s82, 0x18000
	v_lshl_add_u64 v[8:9], v[8:9], 0, s[54:55]
	s_lshl_b32 s14, s4, 7
	s_waitcnt vmcnt(2)
	s_barrier
	global_load_lds_dwordx4 v[8:9], off
	v_lshl_add_u64 v[6:7], v[6:7], 0, s[54:55]
	s_add_i32 m0, s82, 0x1a000
	s_add_i32 s71, s82, 0x8000
	s_add_i32 s72, s82, 0xa000
	v_bitop3_b32 v138, v17, s14, v16 bitop3:0xde
	global_load_lds_dwordx4 v[6:7], off
	v_lshl_add_u64 v[2:3], v[2:3], 0, s[54:55]
	s_mov_b32 m0, s71
	s_add_u32 s14, s26, 0x80080
	global_load_lds_dwordx4 v[2:3], off
	v_lshl_add_u64 v[2:3], v[4:5], 0, s[54:55]
	s_mov_b32 m0, s72
	s_addc_u32 s15, s27, 0
	global_load_lds_dwordx4 v[2:3], off
	s_add_i32 m0, s82, 0x1c000
	v_lshl_add_u64 v[2:3], s[14:15], 0, v[0:1]
	global_load_lds_dwordx4 v[2:3], off
	v_lshl_add_u64 v[2:3], s[14:15], 0, v[130:131]
	s_add_i32 m0, s82, 0x1e000
	s_cmpk_lt_u32 s5, 0x100
	global_load_lds_dwordx4 v[2:3], off
	v_lshlrev_b32_e32 v2, 15, v10
	v_and_b32_e32 v2, 0xffff0000, v2
	v_lshl_add_u32 v2, v11, 12, v2
	v_and_b32_e32 v3, 1, v10
	v_lshl_or_b32 v2, v3, 6, v2
	v_lshl_add_u32 v132, v12, 1, v2
	v_lshlrev_b32_e32 v2, 15, v13
	v_and_b32_e32 v2, 0xffff0000, v2
	v_lshl_add_u32 v2, v14, 12, v2
	v_and_b32_e32 v3, 1, v13
	v_lshl_or_b32 v2, v3, 6, v2
	s_cselect_b64 s[14:15], -1, 0
	v_or_b32_e32 v139, s4, v18
	v_mov_b32_e32 v133, v1
	v_lshl_add_u32 v134, v15, 1, v2
	v_mov_b32_e32 v135, v1
	s_mov_b32 s65, 0
	v_add_u32_e32 v140, 0, v19
	s_branch .LBB0_1057

.LBB0_1059:
	s_ashr_i32 s19, s18, 31
	s_lshl_b64 s[20:21], s[18:19], 20
	s_add_u32 s20, s67, s20
	s_addc_u32 s21, s78, s21
	s_and_b64 s[22:23], s[4:5], exec
	s_cselect_b32 s19, s21, s29
	s_cselect_b32 s33, s20, s28
	s_ashr_i32 s17, s16, 31
	s_lshl_b64 s[22:23], s[16:17], 20
	s_add_u32 s22, s79, s22
	s_addc_u32 s23, s80, s23
	s_and_b64 s[30:31], s[4:5], exec
	s_cselect_b32 s17, s23, s27
	s_cselect_b32 s44, s22, s26
	s_add_u32 s45, s26, 0x100
	s_addc_u32 s48, s27, 0
	s_add_u32 s26, s28, 0x80080
	s_addc_u32 s27, s29, 0
	s_mov_b32 s49, -2
	s_cmp_eq_u32 s99, 0
	s_cbranch_scc0 .Lnofw_G3
	s_waitcnt vmcnt(6)
	s_barrier

.LBB0_1188:
	v_and_b32_e32 v212, 15, v213
	v_and_b32_e32 v18, 48, v213
	v_lshlrev_b32_e32 v19, 2, v213
	s_and_b32 s33, s17, 3
	s_lshl_b32 s34, s4, 6
	s_lshl_b32 s4, s4, 13
	v_lshl_or_b32 v18, v212, 6, v18
	v_and_b32_e32 v19, 32, v19
	s_add_i32 m0, s61, 0x18000
	v_lshl_add_u64 v[8:9], v[8:9], 0, s[54:55]
	s_lshr_b32 s5, s5, 2
	v_bitop3_b32 v20, v18, s4, v19 bitop3:0xde
	s_lshl_b32 s4, s33, 12
	s_waitcnt vmcnt(2)
	s_barrier
	global_load_lds_dwordx4 v[8:9], off
	v_lshl_add_u64 v[6:7], v[6:7], 0, s[54:55]
	s_add_i32 m0, s61, 0x1a000
	s_add_i32 s68, s61, 0x8000
	s_add_i32 s69, s61, 0xa000
	v_bitop3_b32 v140, v18, s4, v19 bitop3:0xde
	global_load_lds_dwordx4 v[6:7], off
	v_lshl_add_u64 v[4:5], v[4:5], 0, s[54:55]
	s_mov_b32 m0, s68
	s_add_u32 s4, s22, 0x160080
	s_sext_i32_i8 s16, s5
	global_load_lds_dwordx4 v[4:5], off
	v_lshl_add_u64 v[2:3], v[2:3], 0, s[54:55]
	s_mov_b32 m0, s69
	s_addc_u32 s5, s23, 0
	global_load_lds_dwordx4 v[2:3], off
	s_add_i32 m0, s61, 0x1c000
	v_lshl_add_u64 v[2:3], s[4:5], 0, v[0:1]
	global_load_lds_dwordx4 v[2:3], off
	v_lshl_add_u64 v[2:3], s[4:5], 0, v[130:131]
	s_add_i32 m0, s61, 0x1e000
	s_movk_i32 s7, 0x1600
	global_load_lds_dwordx4 v[2:3], off
	v_lshrrev_b32_e32 v3, 1, v14
	v_mul_lo_u32 v2, v16, s7
	s_mov_b32 s6, 0x16000
	v_mad_u64_u32 v[2:3], s[4:5], v3, s6, v[2:3]
	v_or_b32_e32 v2, v2, v15
	v_add_lshl_u32 v132, v2, v17, 1
	v_lshrrev_b32_e32 v3, 1, v10
	v_mul_lo_u32 v2, v12, s7
	v_mad_u64_u32 v[2:3], s[4:5], v3, s6, v[2:3]
	v_or_b32_e32 v2, v2, v11
	v_add_lshl_u32 v134, v2, v13, 1
	v_or_b32_e32 v211, s34, v212
	v_mov_b32_e32 v133, v1
	v_mov_b32_e32 v135, v1
	s_mov_b32 s70, 0
	v_add_u32_e32 v141, 0, v20

.LBB0_1199:
	s_add_u32 s74, s22, 0x100
	s_addc_u32 s75, s23, 0
	s_add_u32 s22, s18, 0x160080
	s_addc_u32 s23, s19, 0
	v_lshl_add_u64 v[136:137], s[22:23], 0, v[132:133]
	v_lshl_add_u64 v[138:139], s[22:23], 0, v[134:135]
	s_mov_b32 s76, -2
	s_mov_b64 s[22:23], 0
	s_waitcnt vmcnt(6)
	s_barrier
